# priority level for waves 4-7 around the attention loop raised from 1 to 3 (level sweep)
# speedup vs baseline: 1.0035x; 1.0035x over previous
; #define LAS __attribute__((address_space(3)))
; DI int TID() { int t = threadIdx.x; asm volatile("" : "+v"(t)); return t; }
; template <bool SHIFT> DI void attn_unit(LAS unsigned char* lds, const bf16_t* Qb, const bf16_t* Kb, const bf16_t* Vt, bf16_t* concat,
;                   int b, int h, int qt, float shift2, float lam, int lam_init_bits, const float* subln_g) {
;     const int tid = TID(), wid = __builtin_amdgcn_readfirstlane(tid >> 6), lane = tid & 63, r = lane & 31, hh = lane >> 5;
;     const size_t rowbase = (size_t)b * TPB;
;     const int q0 = qt * 256;
;     const int nkt = (qt == 0) ? 4 : NCH;
;     const bf16_t* kg = Kb + rowbase * 1024 + h * 128;
;     const bf16_t* vg = Vt + ((size_t)(b * 8 + h) * 128) * TPB;
;     const int krow0 = tid >> 4, kc = tid & 15;
;     const int vrow0 = tid >> 3, vc = tid & 7;
; #pragma unroll
;     for (int i = 0; i < 8; ++i) { const int id = i * 512 + tid, row = id >> 4, c = id & 15;
;         const u32x4 v = *(const u32x4*)(Qb + (rowbase + q0 + row) * 1024 + h * 128 + c * 8);
;         *(LAS u32x4*)(lds + Q_OFF + row * QP + c * 16) = v; }
;     u32x4 sg0, sg1;
;     sg0 = *(const u32x4*)(kg + (size_t)(krow0) * 1024 + kc * 8); sg1 = *(const u32x4*)(kg + (size_t)(krow0 + 32) * 1024 + kc * 8);
;     *(LAS u32x4*)(lds + K_OFF + krow0 * QP + kc * 16) = sg0; *(LAS u32x4*)(lds + K_OFF + (krow0 + 32) * QP + kc * 16) = sg1;
;     sg0 = *(const u32x4*)(vg + (size_t)(vrow0) * TPB + vc * 8); sg1 = *(const u32x4*)(vg + (size_t)(vrow0 + 64) * TPB + vc * 8);
;     *(LAS u32x4*)(lds + V_OFF + vrow0 * VP + vc * 16) = sg0; *(LAS u32x4*)(lds + V_OFF + (vrow0 + 64) * VP + vc * 16) = sg1;
;     if (nkt > 1) { sg0 = *(const u32x4*)(kg + (size_t)(64 + krow0) * 1024 + kc * 8); sg1 = *(const u32x4*)(kg + (size_t)(64 + krow0 + 32) * 1024 + kc * 8); }
;     __syncthreads();
;     ...
;     const bool lag = wid >= 4;
.LBB0_532:
	s_mov_b64 s[4:5], s[0:1]
	s_load_dwordx2 s[20:21], s[4:5], 0xa8
	s_mov_b64 s[4:5], s[0:1]
	s_waitcnt lgkmcnt(0)
	s_load_dwordx2 s[4:5], s[4:5], 0xa8
	s_and_b32 s30, s6, 7
	s_mov_b64 s[6:7], s[0:1]
	s_waitcnt lgkmcnt(0)
	s_load_dwordx2 s[6:7], s[6:7], 0xa8
	s_mov_b64 s[12:13], s[0:1]
	s_waitcnt lgkmcnt(0)
	s_mov_b64 s[14:15], s[0:1]
	s_load_dwordx2 s[12:13], s[12:13], 0xa8
	v_mov_b32_e32 v16, v222
	s_lshl_b32 s18, s22, 3
	s_waitcnt lgkmcnt(0)
	s_load_dwordx2 s[16:17], s[14:15], 0x60
	s_or_b32 s34, s18, s30
	v_readfirstlane_b32 s14, v16
	s_lshl_b32 s37, s23, 8
	s_lshl_b32 s29, s30, 7
	s_ashr_i32 s31, s14, 6
	s_mul_i32 s15, s34, 0x210000
	s_mul_hi_i32 s14, s34, 0x210000
	s_add_u32 s15, s6, s15
	s_addc_u32 s14, s7, s14
	s_add_u32 s18, s15, 0x10788000
	s_mul_i32 s36, s22, 0x2100
	s_addc_u32 s19, s14, 0
	s_mul_hi_i32 s35, s22, 0x2100
	s_add_u32 s14, s36, s37
	s_addc_u32 s15, s35, 0
	s_lshl_b32 s37, s30, 8
	s_add_u32 s20, s20, s37
	v_and_b32_e32 v17, 15, v16
	s_addc_u32 s21, s21, 0
	v_lshlrev_b32_e32 v160, 4, v17
	v_mov_b32_e32 v161, v177
	v_ashrrev_i32_e32 v6, 4, v16
	v_lshl_add_u64 v[0:1], s[20:21], 0, v[160:161]
	s_mov_b64 s[20:21], 0xa488000
	v_ashrrev_i32_e32 v7, 31, v6
	v_lshl_add_u64 v[4:5], v[0:1], 0, s[20:21]
	v_lshl_add_u64 v[0:1], s[14:15], 0, v[6:7]
	v_lshlrev_b64 v[0:1], 11, v[0:1]
	v_lshl_add_u64 v[0:1], v[4:5], 0, v[0:1]
	global_load_dwordx4 v[32:35], v[0:1], off
	s_mov_b64 s[20:21], 0x10000
	v_lshl_add_u64 v[64:65], v[0:1], 0, s[20:21]
	global_load_dwordx4 v[36:39], v[64:65], off
	v_lshl_add_u64 v[64:65], v[64:65], 0, s[20:21]
	global_load_dwordx4 v[40:43], v[64:65], off
	v_lshl_add_u64 v[64:65], v[64:65], 0, s[20:21]
	global_load_dwordx4 v[44:47], v[64:65], off
	v_lshl_add_u64 v[64:65], v[64:65], 0, s[20:21]
	global_load_dwordx4 v[48:51], v[64:65], off
	v_lshl_add_u64 v[64:65], v[64:65], 0, s[20:21]
	global_load_dwordx4 v[52:55], v[64:65], off
	v_lshl_add_u64 v[64:65], v[64:65], 0, s[20:21]
	global_load_dwordx4 v[56:59], v[64:65], off
	v_lshl_add_u64 v[64:65], v[64:65], 0, s[20:21]
	global_load_dwordx4 v[60:63], v[64:65], off
	v_add_u32_e32 v8, 0x200, v16
	v_ashrrev_i32_e32 v8, 4, v8
	v_ashrrev_i32_e32 v9, 31, v8
	v_mul_lo_u32 v210, v6, s54
	v_add_u32_e32 v10, 0, v160
	v_lshl_add_u64 v[12:13], s[14:15], 0, v[8:9]
	v_add_u32_e32 v11, v10, v210
	v_mov_b32_e32 v82, v11
	v_lshlrev_b64 v[12:13], 11, v[12:13]
	v_lshl_add_u64 v[12:13], v[4:5], 0, v[12:13]
	v_add_u32_e32 v9, 0x400, v16
	s_mul_i32 s35, s22, 0x1080000
	s_mul_hi_i32 s30, s22, 0x1080000
	v_ashrrev_i32_e32 v18, 3, v16
	v_add_u32_e32 v19, 64, v18
	v_add3_u32 v20, s47, v210, v160
	v_add_u32_e32 v214, 0x2200, v210
	v_add3_u32 v21, s47, v214, v160
	v_mul_lo_u32 v215, v18, s44
	v_add_u32_e32 v216, 0x2400, v215
	v_bfe_u32 v236, v16, 5, 1
	v_lshlrev_b32_e32 v163, 4, v236
	v_lshlrev_b32_e32 v162, 3, v17
	v_mov_b32_e32 v164, 0
	v_mov_b32_e32 v128, 0
	v_mov_b32_e32 v129, 0
	v_mov_b32_e32 v130, 0
	v_mov_b32_e32 v131, 0
	v_mov_b32_e32 v132, 0
	v_mov_b32_e32 v133, 0
	v_mov_b32_e32 v134, 0
	v_mov_b32_e32 v135, 0
	v_mov_b32_e32 v152, 0
	v_mov_b32_e32 v153, 0
	v_mov_b32_e32 v154, 0
	v_mov_b32_e32 v155, 0
	v_mov_b32_e32 v156, 0
	v_mov_b32_e32 v157, 0
	v_mov_b32_e32 v158, 0
	v_mov_b32_e32 v159, 0
	v_mov_b32_e32 v165, v164
	v_ashrrev_i32_e32 v12, 4, v9
	v_ashrrev_i32_e32 v13, 31, v12
	v_lshl_add_u64 v[14:15], s[14:15], 0, v[12:13]
	v_mad_u64_u32 v[8:9], s[20:21], v8, s54, v[10:11]
	v_lshlrev_b64 v[14:15], 11, v[14:15]
	v_lshl_add_u64 v[14:15], v[4:5], 0, v[14:15]
	v_mad_u64_u32 v[12:13], s[20:21], v12, s54, v[10:11]
	v_add_u32_e32 v8, 0x600, v16
	v_ashrrev_i32_e32 v8, 4, v8
	v_ashrrev_i32_e32 v9, 31, v8
	v_lshl_add_u64 v[14:15], s[14:15], 0, v[8:9]
	v_lshlrev_b64 v[14:15], 11, v[14:15]
	v_lshl_add_u64 v[14:15], v[4:5], 0, v[14:15]
	v_add_u32_e32 v9, 0x800, v16
	v_ashrrev_i32_e32 v12, 4, v9
	v_ashrrev_i32_e32 v13, 31, v12
	v_lshl_add_u64 v[14:15], s[14:15], 0, v[12:13]
	v_mad_u64_u32 v[8:9], s[20:21], v8, s54, v[10:11]
	v_lshlrev_b64 v[14:15], 11, v[14:15]
	v_lshl_add_u64 v[14:15], v[4:5], 0, v[14:15]
	v_mad_u64_u32 v[12:13], s[20:21], v12, s54, v[10:11]
	v_add_u32_e32 v8, 0xa00, v16
	v_ashrrev_i32_e32 v8, 4, v8
	v_ashrrev_i32_e32 v9, 31, v8
	v_lshl_add_u64 v[14:15], s[14:15], 0, v[8:9]
	v_lshlrev_b64 v[14:15], 11, v[14:15]
	v_lshl_add_u64 v[14:15], v[4:5], 0, v[14:15]
	v_add_u32_e32 v9, 0xc00, v16
	v_ashrrev_i32_e32 v12, 4, v9
	v_ashrrev_i32_e32 v13, 31, v12
	v_lshl_add_u64 v[14:15], s[14:15], 0, v[12:13]
	v_mad_u64_u32 v[8:9], s[20:21], v8, s54, v[10:11]
	v_lshlrev_b64 v[14:15], 11, v[14:15]
	v_lshl_add_u64 v[14:15], v[4:5], 0, v[14:15]
	v_mad_u64_u32 v[12:13], s[20:21], v12, s54, v[10:11]
	v_add_u32_e32 v8, 0xe00, v16
	v_ashrrev_i32_e32 v8, 4, v8
	v_ashrrev_i32_e32 v9, 31, v8
	v_lshl_add_u64 v[14:15], s[14:15], 0, v[8:9]
	v_lshlrev_b64 v[14:15], 11, v[14:15]
	v_lshl_add_u64 v[4:5], v[4:5], 0, v[14:15]
	v_mad_u64_u32 v[4:5], s[20:21], v8, s54, v[10:11]
	s_add_u32 s20, s4, s35
	s_addc_u32 s21, s5, s30
	s_add_u32 s20, s20, s37
	v_lshlrev_b64 v[12:13], 11, v[6:7]
	s_addc_u32 s21, s21, 0
	v_lshl_add_u64 v[6:7], s[20:21], 0, v[12:13]
	v_lshl_add_u64 v[8:9], v[6:7], 0, v[160:161]
	s_mov_b32 s20, 0xc588000
	v_add_co_u32_e32 v6, vcc, s20, v8
	s_mov_b32 s20, 0xc598000
	s_nop 0
	v_addc_co_u32_e32 v7, vcc, 0, v9, vcc
	v_add_co_u32_e32 v10, vcc, s20, v8
	s_lshl_b32 s30, s31, 5
	s_nop 0
	v_addc_co_u32_e32 v11, vcc, 0, v9, vcc
	s_cmp_gt_i32 s31, 3
	v_and_b32_e32 v161, 63, v16
	global_load_dwordx4 v[66:69], v[6:7], off
	global_load_dwordx4 v[70:73], v[10:11], off
	v_lshlrev_b32_e32 v10, 4, v16
	v_and_b32_e32 v176, 0x70, v10
	v_mov_b64_e32 v[10:11], s[18:19]
	v_mad_i64_i32 v[14:15], s[18:19], v18, s50, v[10:11]
	v_mad_i64_i32 v[10:11], s[18:19], v19, s50, v[10:11]
	v_lshl_add_u64 v[14:15], v[14:15], 0, v[176:177]
	v_lshl_add_u64 v[10:11], v[10:11], 0, v[176:177]
	s_mov_b32 s18, 0xc5a8000
	v_add3_u32 v19, s43, v216, v176
	global_load_dwordx4 v[74:77], v[14:15], off
	global_load_dwordx4 v[78:81], v[10:11], off
	v_add_co_u32_e32 v10, vcc, s18, v8
	v_add3_u32 v15, s43, v215, v176
	s_nop 0
	v_addc_co_u32_e32 v11, vcc, 0, v9, vcc
	s_mov_b32 s18, 0xc5b8000
	v_add_co_u32_e32 v8, vcc, s18, v8
	v_and_b32_e32 v14, 31, v16
	s_nop 0
	v_addc_co_u32_e32 v9, vcc, 0, v9, vcc
	s_mov_b64 s[18:19], -1
	s_cmp_lt_i32 s31, 4
	s_mov_b64 s[20:21], 0
	s_cmp_gt_i32 s31, 3
	s_cbranch_scc0 .Lattn_noprio
	s_setprio 3
